# attention softmax: s-m and the row-sum partial sums with packed f32 adds (v_pk_add_f32), 8 fewer VALU per 8 scores
# baseline (speedup 1.0000x reference)
; DI unsigned pk2(float a, float b) { f32x2_t f = {a, b}; return __builtin_bit_cast(unsigned, __builtin_convertvector(f, bf16x2_t)); }
; DI void attn_item(const u16* __restrict__ qbuf, const u16* __restrict__ knope, const u16* __restrict__ krope, ...
;     ...
;       const float m_new = fmaxf(m_run, mx);
;       const float alpha = __builtin_amdgcn_exp2f(m_run - m_new);
;       m_run = m_new;
;       float ps = 0.f;
; #pragma unroll
;       for (int mt = 0; mt < 2; ++mt)
; #pragma unroll
;         for (int j = 0; j < 16; ++j) { const float pv = __builtin_amdgcn_exp2f(st[mt][j] - m_new); st[mt][j] = pv; ps += pv; }
;       l_run = l_run * alpha + ps;
;     ...
; #pragma unroll
;       for (int mt = 0; mt < 2; ++mt)
; #pragma unroll
;         for (int s = 0; s < 2; ++s) {
;           union { bf16x8 v; unsigned u[4]; } pf;
; #pragma unroll
;           for (int k = 0; k < 4; ++k) pf.u[k] = pk2(st[mt][8 * s + 2 * k], st[mt][8 * s + 2 * k + 1]);
; #pragma unroll
;           for (int vt4 = 0; vt4 < 4; ++vt4) {
;             const bf16x8 vf = *(const bf16x8*)(cur + 24576 + koff[mt * 2 + s] + vt4 * 4096);
;             oacc[vt4] = __builtin_amdgcn_mfma_f32_32x32x16_bf16(vf, pf.v, oacc[vt4], 0, 0, 0);
;           }
.LBB0_49:
	v_xor_b32_e32 v174, 0x80000000, v157
	v_xor_b32_e32 v175, 0x80000000, v157
	v_pk_add_f32 v[64:65], v[64:65], v[174:175]
	v_pk_add_f32 v[66:67], v[66:67], v[174:175]
	v_pk_add_f32 v[68:69], v[68:69], v[174:175]
	v_pk_add_f32 v[70:71], v[70:71], v[174:175]
	v_exp_f32_e32 v64, v64
	v_exp_f32_e32 v65, v65
	v_exp_f32_e32 v66, v66
	v_exp_f32_e32 v67, v67
	v_exp_f32_e32 v68, v68
	v_exp_f32_e32 v69, v69
	v_exp_f32_e32 v70, v70
	v_exp_f32_e32 v71, v71
	v_pk_add_f32 v[176:177], v[64:65], v[66:67]
	v_pk_add_f32 v[178:179], v[68:69], v[70:71]
	v_cvt_pk_bf16_f32 v64, v64, v65
	v_cvt_pk_bf16_f32 v65, v66, v67
	v_pk_add_f32 v[180:181], v[176:177], v[178:179]
	v_cvt_pk_bf16_f32 v66, v68, v69
	v_cvt_pk_bf16_f32 v67, v70, v71
	v_nop
	s_waitcnt lgkmcnt(7)
	v_mfma_f32_32x32x16_bf16 v[48:63], v[224:227], v[64:67], v[48:63]
	ds_read_b128 v[224:227], v163 offset:24576
	v_pk_add_f32 v[72:73], v[72:73], v[174:175]
	v_pk_add_f32 v[74:75], v[74:75], v[174:175]
	v_pk_add_f32 v[76:77], v[76:77], v[174:175]
	v_pk_add_f32 v[78:79], v[78:79], v[174:175]
	v_exp_f32_e32 v72, v72
	s_waitcnt lgkmcnt(7)
	v_mfma_f32_32x32x16_bf16 v[32:47], v[228:231], v[64:67], v[32:47]
	ds_read_b128 v[228:231], v163 offset:28672
	v_exp_f32_e32 v73, v73
	v_exp_f32_e32 v74, v74
	v_exp_f32_e32 v75, v75
	v_exp_f32_e32 v76, v76
	v_exp_f32_e32 v77, v77
	s_waitcnt lgkmcnt(7)
	v_mfma_f32_32x32x16_bf16 v[16:31], v[232:235], v[64:67], v[16:31]
	ds_read_b128 v[232:235], v163 offset:32768
	v_exp_f32_e32 v78, v78
	v_exp_f32_e32 v79, v79
	v_pk_add_f32 v[176:177], v[72:73], v[74:75]
	v_pk_add_f32 v[178:179], v[76:77], v[78:79]
	v_cvt_pk_bf16_f32 v72, v72, v73
	s_waitcnt lgkmcnt(7)
	v_mfma_f32_32x32x16_bf16 v[0:15], v[236:239], v[64:67], v[0:15]
	ds_read_b128 v[236:239], v163 offset:36864
	v_cvt_pk_bf16_f32 v73, v74, v75
	v_pk_add_f32 v[176:177], v[176:177], v[178:179]
	v_cvt_pk_bf16_f32 v74, v76, v77
	v_cvt_pk_bf16_f32 v75, v78, v79
	v_pk_add_f32 v[180:181], v[180:181], v[176:177]
	s_waitcnt lgkmcnt(7)
	v_mfma_f32_32x32x16_bf16 v[48:63], v[240:243], v[72:75], v[48:63]
	ds_read_b128 v[240:243], v164 offset:24576
	v_pk_add_f32 v[80:81], v[80:81], v[174:175]
	v_pk_add_f32 v[82:83], v[82:83], v[174:175]
	v_pk_add_f32 v[84:85], v[84:85], v[174:175]
	v_pk_add_f32 v[86:87], v[86:87], v[174:175]
	v_exp_f32_e32 v80, v80
	s_waitcnt lgkmcnt(7)
	v_mfma_f32_32x32x16_bf16 v[32:47], v[244:247], v[72:75], v[32:47]
	ds_read_b128 v[244:247], v164 offset:28672
	v_exp_f32_e32 v81, v81
	v_exp_f32_e32 v82, v82
	v_exp_f32_e32 v83, v83
	v_exp_f32_e32 v84, v84
	v_exp_f32_e32 v85, v85
	s_waitcnt lgkmcnt(7)
	v_mfma_f32_32x32x16_bf16 v[16:31], v[248:251], v[72:75], v[16:31]
	ds_read_b128 v[248:251], v164 offset:32768
	v_exp_f32_e32 v86, v86
	v_exp_f32_e32 v87, v87
	v_pk_add_f32 v[176:177], v[80:81], v[82:83]
	v_pk_add_f32 v[178:179], v[84:85], v[86:87]
	v_cvt_pk_bf16_f32 v80, v80, v81
	s_waitcnt lgkmcnt(7)
	v_mfma_f32_32x32x16_bf16 v[0:15], v[186:189], v[72:75], v[0:15]
	ds_read_b128 v[186:189], v164 offset:36864
	v_cvt_pk_bf16_f32 v81, v82, v83
	v_pk_add_f32 v[176:177], v[176:177], v[178:179]
	v_cvt_pk_bf16_f32 v82, v84, v85
	v_cvt_pk_bf16_f32 v83, v86, v87
	v_pk_add_f32 v[180:181], v[180:181], v[176:177]
	s_waitcnt lgkmcnt(7)
	v_mfma_f32_32x32x16_bf16 v[48:63], v[224:227], v[80:83], v[48:63]
	v_pk_add_f32 v[88:89], v[88:89], v[174:175]
	v_pk_add_f32 v[90:91], v[90:91], v[174:175]
	v_pk_add_f32 v[92:93], v[92:93], v[174:175]
	v_pk_add_f32 v[94:95], v[94:95], v[174:175]
	v_exp_f32_e32 v88, v88
	s_waitcnt lgkmcnt(6)
	v_mfma_f32_32x32x16_bf16 v[32:47], v[228:231], v[80:83], v[32:47]
	v_exp_f32_e32 v89, v89
	v_exp_f32_e32 v90, v90
	v_exp_f32_e32 v91, v91
	v_exp_f32_e32 v92, v92
	v_exp_f32_e32 v93, v93
	s_waitcnt lgkmcnt(5)
	v_mfma_f32_32x32x16_bf16 v[16:31], v[232:235], v[80:83], v[16:31]
	v_exp_f32_e32 v94, v94
	v_exp_f32_e32 v95, v95
	v_pk_add_f32 v[176:177], v[88:89], v[90:91]
	v_pk_add_f32 v[178:179], v[92:93], v[94:95]
	v_cvt_pk_bf16_f32 v88, v88, v89
	s_waitcnt lgkmcnt(4)
	v_mfma_f32_32x32x16_bf16 v[0:15], v[236:239], v[80:83], v[0:15]
	v_cvt_pk_bf16_f32 v89, v90, v91
	v_pk_add_f32 v[176:177], v[176:177], v[178:179]
	v_cvt_pk_bf16_f32 v90, v92, v93
	v_cvt_pk_bf16_f32 v91, v94, v95
	v_pk_add_f32 v[180:181], v[180:181], v[176:177]
	s_waitcnt lgkmcnt(3)
	v_mfma_f32_32x32x16_bf16 v[48:63], v[240:243], v[88:91], v[48:63]
	v_add_f32_e32 v160, v180, v181
	s_waitcnt lgkmcnt(2)
	v_mfma_f32_32x32x16_bf16 v[32:47], v[244:247], v[88:91], v[32:47]
	v_fmac_f32_e32 v160, v151, v146
	s_waitcnt lgkmcnt(1)
	v_mfma_f32_32x32x16_bf16 v[16:31], v[248:251], v[88:91], v[16:31]
	v_mov_b32_e32 v146, v157
	s_waitcnt lgkmcnt(0)
	v_mfma_f32_32x32x16_bf16 v[0:15], v[186:189], v[88:91], v[0:15]
	v_mov_b32_e32 v151, v160

; DI unsigned pk2(float a, float b) { f32x2_t f = {a, b}; return __builtin_bit_cast(unsigned, __builtin_convertvector(f, bf16x2_t)); }
; DI void attn_item(const u16* __restrict__ qbuf, const u16* __restrict__ knope, const u16* __restrict__ krope, ...
;     ...
;       const float m_new = fmaxf(m_run, mx);
;       const float alpha = __builtin_amdgcn_exp2f(m_run - m_new);
;       m_run = m_new;
;       float ps = 0.f;
; #pragma unroll
;       for (int mt = 0; mt < 2; ++mt)
; #pragma unroll
;         for (int j = 0; j < 16; ++j) { const float pv = __builtin_amdgcn_exp2f(st[mt][j] - m_new); st[mt][j] = pv; ps += pv; }
;       l_run = l_run * alpha + ps;
;       if (__any(alpha != 1.f)) {
; #pragma unroll
;         for (int i = 0; i < 4; ++i)
; #pragma unroll
;           for (int j = 0; j < 16; ++j) oacc[i][j] *= alpha;
;       }
; #pragma unroll
;       for (int mt = 0; mt < 2; ++mt)
; #pragma unroll
;         for (int s = 0; s < 2; ++s) {
;           union { bf16x8 v; unsigned u[4]; } pf;
; #pragma unroll
;           for (int k = 0; k < 4; ++k) pf.u[k] = pk2(st[mt][8 * s + 2 * k], st[mt][8 * s + 2 * k + 1]);
; #pragma unroll
;           for (int vt4 = 0; vt4 < 4; ++vt4) {
;             const bf16x8 vf = *(const bf16x8*)(cur + 24576 + koff[mt * 2 + s] + vt4 * 4096);
;             oacc[vt4] = __builtin_amdgcn_mfma_f32_32x32x16_bf16(vf, pf.v, oacc[vt4], 0, 0, 0);
;           }
;         }
.LBB0_72:
	v_xor_b32_e32 v174, 0x80000000, v165
	v_xor_b32_e32 v175, 0x80000000, v165
	v_pk_add_f32 v[64:65], v[64:65], v[174:175]
	v_pk_add_f32 v[66:67], v[66:67], v[174:175]
	v_pk_add_f32 v[68:69], v[68:69], v[174:175]
	v_pk_add_f32 v[70:71], v[70:71], v[174:175]
	v_exp_f32_e32 v64, v64
	v_exp_f32_e32 v65, v65
	v_exp_f32_e32 v66, v66
	v_exp_f32_e32 v67, v67
	v_exp_f32_e32 v68, v68
	v_exp_f32_e32 v69, v69
	v_exp_f32_e32 v70, v70
	v_exp_f32_e32 v71, v71
	v_pk_add_f32 v[176:177], v[64:65], v[66:67]
	v_pk_add_f32 v[178:179], v[68:69], v[70:71]
	v_cvt_pk_bf16_f32 v64, v64, v65
	v_cvt_pk_bf16_f32 v65, v66, v67
	v_pk_add_f32 v[180:181], v[176:177], v[178:179]
	v_cvt_pk_bf16_f32 v66, v68, v69
	v_cvt_pk_bf16_f32 v67, v70, v71
	v_nop
	s_waitcnt lgkmcnt(7)
	v_mfma_f32_32x32x16_bf16 v[48:63], v[224:227], v[64:67], v[48:63]
	ds_read_b128 v[224:227], v171 offset:24576
	v_pk_add_f32 v[72:73], v[72:73], v[174:175]
	v_pk_add_f32 v[74:75], v[74:75], v[174:175]
	v_pk_add_f32 v[76:77], v[76:77], v[174:175]
	v_pk_add_f32 v[78:79], v[78:79], v[174:175]
	v_exp_f32_e32 v72, v72
	s_waitcnt lgkmcnt(7)
	v_mfma_f32_32x32x16_bf16 v[32:47], v[228:231], v[64:67], v[32:47]
	ds_read_b128 v[228:231], v171 offset:28672
	v_exp_f32_e32 v73, v73
	v_exp_f32_e32 v74, v74
	v_exp_f32_e32 v75, v75
	v_exp_f32_e32 v76, v76
	v_exp_f32_e32 v77, v77
	s_waitcnt lgkmcnt(7)
	v_mfma_f32_32x32x16_bf16 v[16:31], v[232:235], v[64:67], v[16:31]
	ds_read_b128 v[232:235], v171 offset:32768
	v_exp_f32_e32 v78, v78
	v_exp_f32_e32 v79, v79
	v_pk_add_f32 v[176:177], v[72:73], v[74:75]
	v_pk_add_f32 v[178:179], v[76:77], v[78:79]
	v_cvt_pk_bf16_f32 v72, v72, v73
	s_waitcnt lgkmcnt(7)
	v_mfma_f32_32x32x16_bf16 v[0:15], v[236:239], v[64:67], v[0:15]
	ds_read_b128 v[236:239], v171 offset:36864
	v_cvt_pk_bf16_f32 v73, v74, v75
	v_pk_add_f32 v[176:177], v[176:177], v[178:179]
	v_cvt_pk_bf16_f32 v74, v76, v77
	v_cvt_pk_bf16_f32 v75, v78, v79
	v_pk_add_f32 v[180:181], v[180:181], v[176:177]
	s_waitcnt lgkmcnt(7)
	v_mfma_f32_32x32x16_bf16 v[48:63], v[240:243], v[72:75], v[48:63]
	ds_read_b128 v[240:243], v172 offset:24576
	v_pk_add_f32 v[80:81], v[80:81], v[174:175]
	v_pk_add_f32 v[82:83], v[82:83], v[174:175]
	v_pk_add_f32 v[84:85], v[84:85], v[174:175]
	v_pk_add_f32 v[86:87], v[86:87], v[174:175]
	v_exp_f32_e32 v80, v80
	s_waitcnt lgkmcnt(7)
	v_mfma_f32_32x32x16_bf16 v[32:47], v[244:247], v[72:75], v[32:47]
	ds_read_b128 v[244:247], v172 offset:28672
	v_exp_f32_e32 v81, v81
	v_exp_f32_e32 v82, v82
	v_exp_f32_e32 v83, v83
	v_exp_f32_e32 v84, v84
	v_exp_f32_e32 v85, v85
	s_waitcnt lgkmcnt(7)
	v_mfma_f32_32x32x16_bf16 v[16:31], v[248:251], v[72:75], v[16:31]
	ds_read_b128 v[248:251], v172 offset:32768
	v_exp_f32_e32 v86, v86
	v_exp_f32_e32 v87, v87
	v_pk_add_f32 v[176:177], v[80:81], v[82:83]
	v_pk_add_f32 v[178:179], v[84:85], v[86:87]
	v_cvt_pk_bf16_f32 v80, v80, v81
	s_waitcnt lgkmcnt(7)
	v_mfma_f32_32x32x16_bf16 v[0:15], v[186:189], v[72:75], v[0:15]
	ds_read_b128 v[186:189], v172 offset:36864
	v_cvt_pk_bf16_f32 v81, v82, v83
	v_pk_add_f32 v[176:177], v[176:177], v[178:179]
	v_cvt_pk_bf16_f32 v82, v84, v85
	v_cvt_pk_bf16_f32 v83, v86, v87
	v_pk_add_f32 v[180:181], v[180:181], v[176:177]
	s_waitcnt lgkmcnt(7)
	v_mfma_f32_32x32x16_bf16 v[48:63], v[224:227], v[80:83], v[48:63]
	v_pk_add_f32 v[88:89], v[88:89], v[174:175]
	v_pk_add_f32 v[90:91], v[90:91], v[174:175]
	v_pk_add_f32 v[92:93], v[92:93], v[174:175]
	v_pk_add_f32 v[94:95], v[94:95], v[174:175]
	v_exp_f32_e32 v88, v88
	s_waitcnt lgkmcnt(6)
	v_mfma_f32_32x32x16_bf16 v[32:47], v[228:231], v[80:83], v[32:47]
	v_exp_f32_e32 v89, v89
	v_exp_f32_e32 v90, v90
	v_exp_f32_e32 v91, v91
	v_exp_f32_e32 v92, v92
	v_exp_f32_e32 v93, v93
	s_waitcnt lgkmcnt(5)
	v_mfma_f32_32x32x16_bf16 v[16:31], v[232:235], v[80:83], v[16:31]
	v_exp_f32_e32 v94, v94
	v_exp_f32_e32 v95, v95
	v_pk_add_f32 v[176:177], v[88:89], v[90:91]
	v_pk_add_f32 v[178:179], v[92:93], v[94:95]
	v_cvt_pk_bf16_f32 v88, v88, v89
	s_waitcnt lgkmcnt(4)
	v_mfma_f32_32x32x16_bf16 v[0:15], v[236:239], v[80:83], v[0:15]
	v_cvt_pk_bf16_f32 v89, v90, v91
	v_pk_add_f32 v[176:177], v[176:177], v[178:179]
	v_cvt_pk_bf16_f32 v90, v92, v93
	v_cvt_pk_bf16_f32 v91, v94, v95
	v_pk_add_f32 v[180:181], v[180:181], v[176:177]
	s_waitcnt lgkmcnt(3)
	v_mfma_f32_32x32x16_bf16 v[48:63], v[240:243], v[88:91], v[48:63]
	v_add_f32_e32 v168, v180, v181
	s_waitcnt lgkmcnt(2)
	v_mfma_f32_32x32x16_bf16 v[32:47], v[244:247], v[88:91], v[32:47]
	v_fmac_f32_e32 v168, v164, v146
	s_waitcnt lgkmcnt(1)
	v_mfma_f32_32x32x16_bf16 v[16:31], v[248:251], v[88:91], v[16:31]
	v_mov_b32_e32 v146, v165
	s_waitcnt lgkmcnt(0)
	v_mfma_f32_32x32x16_bf16 v[0:15], v[186:189], v[88:91], v[0:15]
	v_mov_b32_e32 v164, v168
	s_or_b64 exec, exec, s[84:85]
	s_add_i32 s15, s15, 64
	s_cmp_eq_u32 s13, s16
	s_cbranch_scc1 .LBB0_75
